# attention QK: the first tile's score MFMAs reordered so each accumulator's K-steps 0,1 and 2,3 are back-to-back accumulate chains (two adjacent swaps)
# speedup vs baseline: 1.0082x; 1.0082x over previous
.Lqpf_skip:
	s_cmp_gt_u32 s13, 9
	s_waitcnt lgkmcnt(0)
	s_barrier
	s_cbranch_scc1 .LBB0_1072
	s_add_i32 s26, s21, s22
	s_cmp_lg_u32 s13, 9
	s_cselect_b32 s27, s26, 0xfffffd80
	v_add_u32_e32 v152, s25, v174
	v_lshl_add_u32 v44, s27, 2, v133
	ds_read_b128 v[32:35], v152
	ds_read_b128 v[64:67], v44 offset:2816
	ds_read_b128 v[68:71], v44 offset:2848
	ds_read_b128 v[72:75], v44 offset:2880
	ds_read_b128 v[76:79], v44 offset:2912
	ds_read_b128 v[36:39], v152 offset:4608
	ds_read_b128 v[40:43], v152 offset:32
	s_waitcnt lgkmcnt(2)
	v_mfma_f32_32x32x16_bf16 v[64:79], v[32:35], v[96:99], v[64:79]
	ds_read_b128 v[80:83], v44 offset:2944
	ds_read_b128 v[84:87], v44 offset:2976
	ds_read_b128 v[88:91], v44 offset:3008
	ds_read_b128 v[92:95], v44 offset:3040
	ds_read_b128 v[32:35], v152 offset:4640
	s_add_i32 s26, s26, 64
	s_cmp_lg_u32 s13, 0
	s_cselect_b32 s25, s26, 0xfffffd80
	v_lshl_add_u32 v60, s25, 2, v133
	v_add_u32_e32 v179, s24, v135
	s_waitcnt lgkmcnt(1)
	v_mfma_f32_32x32x16_bf16 v[64:79], v[40:43], v[100:103], v[64:79]
	v_mfma_f32_32x32x16_bf16 v[80:95], v[36:39], v[96:99], v[80:95]
	s_waitcnt lgkmcnt(0)
	v_mfma_f32_32x32x16_bf16 v[80:95], v[32:35], v[100:103], v[80:95]
	ds_read_b128 v[32:35], v152 offset:64
	ds_read_b128 v[36:39], v152 offset:96
	s_waitcnt lgkmcnt(1)
	v_mfma_f32_32x32x16_bf16 v[64:79], v[32:35], v[104:107], v[64:79]
	ds_read_b128 v[32:35], v152 offset:4672
	ds_read_b128 v[48:51], v152 offset:4704
	s_waitcnt lgkmcnt(1)
	v_mfma_f32_32x32x16_bf16 v[64:79], v[36:39], v[108:111], v[64:79]
	v_mfma_f32_32x32x16_bf16 v[80:95], v[32:35], v[104:107], v[80:95]
	ds_read_b128 v[32:35], v60 offset:2816
	ds_read_b128 v[36:39], v60 offset:2848
	ds_read_b128 v[40:43], v60 offset:2880
	ds_read_b128 v[44:47], v60 offset:2912
	ds_read_b128 v[140:143], v152 offset:9216
	s_nop 6
	v_exp_f32_e32 v168, v64
	s_waitcnt lgkmcnt(5)
	v_mfma_f32_32x32x16_bf16 v[80:95], v[48:51], v[108:111], v[80:95]
	ds_read_b128 v[48:51], v60 offset:2944
	ds_read_b128 v[52:55], v60 offset:2976
	ds_read_b128 v[56:59], v60 offset:3008
	ds_read_b128 v[60:63], v60 offset:3040
	ds_read_b128 v[144:147], v152 offset:9248
	ds_read_b128 v[148:151], v152 offset:13824
	ds_read_b128 v[180:183], v152 offset:13856
	ds_read_b128 v[184:187], v152 offset:9280
	ds_read_b128 v[188:191], v152 offset:9312
	ds_read_b128 v[192:195], v152 offset:13888
	ds_read_b128 v[196:199], v152 offset:13920
	v_exp_f32_e32 v156, v65
	v_exp_f32_e32 v158, v66
	v_exp_f32_e32 v162, v67
	v_exp_f32_e32 v216, v68
	v_exp_f32_e32 v76, v76
	s_waitcnt lgkmcnt(5)
	v_mfma_f32_32x32x16_bf16 v[48:63], v[148:151], v[96:99], v[48:63]
	v_exp_f32_e32 v148, v71
	v_exp_f32_e32 v170, v80
	v_exp_f32_e32 v164, v82
	v_exp_f32_e32 v150, v86
	v_exp_f32_e32 v80, v72
	v_exp_f32_e32 v82, v73
	v_exp_f32_e32 v86, v74
	s_waitcnt lgkmcnt(4)
	v_mfma_f32_32x32x16_bf16 v[48:63], v[180:183], v[100:103], v[48:63]
	v_cvt_pk_bf16_f32 v180, v168, v156
	v_cvt_pk_bf16_f32 v181, v158, v162
	v_exp_f32_e32 v64, v77
	v_exp_f32_e32 v66, v78
	v_exp_f32_e32 v160, v81
	v_exp_f32_e32 v166, v83
	v_exp_f32_e32 v172, v84
	v_mfma_f32_32x32x16_bf16 v[32:47], v[140:143], v[96:99], v[32:47]
	v_exp_f32_e32 v140, v69
	v_exp_f32_e32 v142, v70
	v_exp_f32_e32 v70, v79
	v_exp_f32_e32 v154, v87
	v_cvt_pk_bf16_f32 v182, v216, v140
	v_cvt_pk_bf16_f32 v183, v142, v148
	v_exp_f32_e32 v84, v88
	s_waitcnt lgkmcnt(1)
	v_mfma_f32_32x32x16_bf16 v[48:63], v[192:195], v[104:107], v[48:63]
	ds_read_b64_tr_b16 v[192:193], v179 offset:36864
	ds_read_b64_tr_b16 v[194:195], v179 offset:38400
	ds_read_b64_tr_b16 v[202:203], v179 offset:38464
	ds_read_b64_tr_b16 v[200:201], v179 offset:36928
	v_exp_f32_e32 v88, v89
	v_exp_f32_e32 v152, v91
	v_exp_f32_e32 v92, v92
	v_exp_f32_e32 v68, v93
	v_exp_f32_e32 v72, v94
	v_mfma_f32_32x32x16_bf16 v[32:47], v[144:147], v[100:103], v[32:47]
	v_exp_f32_e32 v146, v90
	v_exp_f32_e32 v90, v75
	v_exp_f32_e32 v144, v85
	v_exp_f32_e32 v74, v95
	s_waitcnt lgkmcnt(0)
	v_mfma_f32_32x32x16_bf16 v[16:31], v[200:203], v[180:183], v[16:31]
	v_mfma_f32_32x32x16_bf16 v[0:15], v[192:195], v[180:183], v[0:15]
	ds_read_b64_tr_b16 v[192:193], v179 offset:39936
	ds_read_b64_tr_b16 v[194:195], v179 offset:41472
	ds_read_b64_tr_b16 v[206:207], v179 offset:41536
	ds_read_b64_tr_b16 v[204:205], v179 offset:40000
	ds_read_b64_tr_b16 v[208:209], v179 offset:43008
	ds_read_b64_tr_b16 v[210:211], v179 offset:44544
	ds_read_b64_tr_b16 v[214:215], v179 offset:44608
	ds_read_b64_tr_b16 v[212:213], v179 offset:43072
	ds_read_b64_tr_b16 v[180:181], v179 offset:46080
	ds_read_b64_tr_b16 v[182:183], v179 offset:47616
	ds_read_b64_tr_b16 v[202:203], v179 offset:47680
	ds_read_b64_tr_b16 v[200:201], v179 offset:46144
	v_mfma_f32_32x32x16_bf16 v[32:47], v[184:187], v[104:107], v[32:47]
	v_cvt_pk_bf16_f32 v184, v80, v82
	v_cvt_pk_bf16_f32 v185, v86, v90
	v_cvt_pk_bf16_f32 v186, v76, v64
	v_cvt_pk_bf16_f32 v187, v66, v70
	s_waitcnt lgkmcnt(8)
	s_nop 0
	v_mfma_f32_32x32x16_bf16 v[16:31], v[204:207], v[184:187], v[16:31]
	v_mfma_f32_32x32x16_bf16 v[0:15], v[192:195], v[184:187], v[0:15]
	v_mfma_f32_32x32x16_bf16 v[32:47], v[188:191], v[108:111], v[32:47]
	v_cvt_pk_bf16_f32 v188, v170, v160
	v_cvt_pk_bf16_f32 v189, v164, v166
	v_cvt_pk_bf16_f32 v190, v172, v144
	v_cvt_pk_bf16_f32 v191, v150, v154
	s_waitcnt lgkmcnt(4)
	s_nop 0
	v_mfma_f32_32x32x16_bf16 v[16:31], v[212:215], v[188:191], v[16:31]
	s_nop 4
	v_exp_f32_e32 v169, v32
	v_exp_f32_e32 v157, v33
	v_exp_f32_e32 v159, v34
	v_exp_f32_e32 v217, v36
	v_exp_f32_e32 v163, v35
	v_exp_f32_e32 v141, v37
	v_exp_f32_e32 v143, v38
	v_mfma_f32_32x32x16_bf16 v[0:15], v[208:211], v[188:191], v[0:15]
	v_exp_f32_e32 v149, v39
	v_exp_f32_e32 v81, v40
	v_exp_f32_e32 v83, v41
	v_exp_f32_e32 v87, v42
	v_exp_f32_e32 v91, v43
	ds_read_b64_tr_b16 v[40:41], v179 offset:49152
	ds_read_b64_tr_b16 v[42:43], v179 offset:50688
	v_cvt_pk_bf16_f32 v32, v169, v157
	v_mfma_f32_32x32x16_bf16 v[48:63], v[196:199], v[108:111], v[48:63]
	v_cvt_pk_bf16_f32 v196, v84, v88
	v_cvt_pk_bf16_f32 v197, v146, v152
	v_cvt_pk_bf16_f32 v198, v92, v68
	v_cvt_pk_bf16_f32 v199, v72, v74
	v_cvt_pk_bf16_f32 v33, v159, v163
	v_cvt_pk_bf16_f32 v34, v217, v141
	v_cvt_pk_bf16_f32 v35, v143, v149
	s_waitcnt lgkmcnt(2)
	v_mfma_f32_32x32x16_bf16 v[16:31], v[200:203], v[196:199], v[16:31]
	s_nop 2
	v_exp_f32_e32 v171, v48
	v_exp_f32_e32 v161, v49
	v_exp_f32_e32 v165, v50
	v_exp_f32_e32 v167, v51
	ds_read_b64_tr_b16 v[50:51], v179 offset:50752
	ds_read_b64_tr_b16 v[48:49], v179 offset:49216
	v_exp_f32_e32 v85, v56
	v_exp_f32_e32 v89, v57
	v_mfma_f32_32x32x16_bf16 v[0:15], v[180:183], v[196:199], v[0:15]
	v_add_f32_e64 v56, v168, v170
	v_add_f32_e64 v57, v169, v171
	v_exp_f32_e32 v173, v52
	v_exp_f32_e32 v145, v53
	v_exp_f32_e32 v151, v54
	v_exp_f32_e32 v155, v55
	v_exp_f32_e32 v77, v44
	v_exp_f32_e32 v65, v45
	s_waitcnt lgkmcnt(0)
	v_mfma_f32_32x32x16_bf16 v[16:31], v[48:51], v[32:35], v[16:31]
	v_exp_f32_e32 v67, v46
	v_exp_f32_e32 v71, v47
	ds_read_b64_tr_b16 v[52:53], v179 offset:52224
	ds_read_b64_tr_b16 v[54:55], v179 offset:53760
	v_cvt_pk_bf16_f32 v36, v81, v83
	v_cvt_pk_bf16_f32 v37, v87, v91
	v_cvt_pk_bf16_f32 v38, v77, v65
	v_cvt_pk_bf16_f32 v39, v67, v71
	v_mfma_f32_32x32x16_bf16 v[0:15], v[40:43], v[32:35], v[0:15]
	v_add_f32_e64 v32, v156, v160
	v_add_f32_e64 v33, v157, v161
	v_add_f32_e32 v56, v32, v56
	v_add_f32_e32 v57, v33, v57
	v_add_f32_e64 v48, v158, v164
	v_add_f32_e64 v49, v159, v165
	ds_read_b64_tr_b16 v[34:35], v179 offset:53824
	ds_read_b64_tr_b16 v[32:33], v179 offset:52288
	v_add_f32_e32 v50, v162, v166
	v_add_f32_e32 v51, v163, v167
	v_add_f32_e32 v48, v48, v56
	v_add_f32_e32 v49, v49, v57
	s_waitcnt lgkmcnt(0)
	v_mfma_f32_32x32x16_bf16 v[16:31], v[32:35], v[36:39], v[16:31]
	v_add_f32_e64 v78, v216, v172
	v_add_f32_e64 v79, v217, v173
	v_exp_f32_e32 v147, v58
	v_cvt_pk_bf16_f32 v44, v171, v161
	v_cvt_pk_bf16_f32 v45, v165, v167
	v_cvt_pk_bf16_f32 v46, v173, v145
	v_cvt_pk_bf16_f32 v47, v151, v155
	v_add_f32_e32 v56, v142, v150
	v_add_f32_e32 v57, v143, v151
	v_mfma_f32_32x32x16_bf16 v[0:15], v[52:55], v[36:39], v[0:15]
	v_add_f32_e64 v52, v50, v48
	v_add_f32_e64 v53, v51, v49
	ds_read_b64_tr_b16 v[48:49], v179 offset:55296
	ds_read_b64_tr_b16 v[50:51], v179 offset:56832
	ds_read_b64_tr_b16 v[34:35], v179 offset:56896
	ds_read_b64_tr_b16 v[32:33], v179 offset:55360
	v_add_f32_e32 v54, v140, v144
	v_add_f32_e32 v55, v141, v145
	v_add_f32_e32 v36, v78, v52
	v_add_f32_e32 v37, v79, v53
	v_exp_f32_e32 v153, v59
	v_add_f32_e32 v52, v54, v36
	v_add_f32_e32 v53, v55, v37
	v_add_f32_e32 v58, v148, v154
	v_add_f32_e32 v59, v149, v155
	s_waitcnt lgkmcnt(0)
	v_mfma_f32_32x32x16_bf16 v[16:31], v[32:35], v[44:47], v[16:31]
	v_add_f32_e64 v32, v56, v52
	v_add_f32_e64 v33, v57, v53
	v_exp_f32_e32 v93, v60
	v_exp_f32_e32 v69, v61
	v_add_f32_e32 v60, v80, v84
	v_add_f32_e32 v61, v81, v85
	v_add_f32_e32 v32, v58, v32
	v_add_f32_e32 v33, v59, v33
	v_exp_f32_e32 v73, v62
	v_exp_f32_e32 v75, v63
	v_mfma_f32_32x32x16_bf16 v[0:15], v[48:51], v[44:47], v[0:15]
	v_add_f32_e64 v62, v82, v88
	v_add_f32_e64 v63, v83, v89
	v_add_f32_e64 v32, v60, v32
	v_add_f32_e64 v33, v61, v33
	v_add_f32_e64 v80, v86, v146
	v_add_f32_e64 v81, v87, v147
	v_add_f32_e32 v32, v62, v32
	v_add_f32_e32 v33, v63, v33
	ds_read_b64_tr_b16 v[36:37], v179 offset:58368
	ds_read_b64_tr_b16 v[38:39], v179 offset:59904
	v_add_f32_e32 v44, v80, v32
	v_add_f32_e32 v45, v81, v33
	ds_read_b64_tr_b16 v[34:35], v179 offset:59968
	ds_read_b64_tr_b16 v[32:33], v179 offset:58432
	v_cvt_pk_bf16_f32 v40, v85, v89
	v_cvt_pk_bf16_f32 v41, v147, v153
	v_cvt_pk_bf16_f32 v42, v93, v69
	v_cvt_pk_bf16_f32 v43, v73, v75
	v_add_f32_e32 v82, v90, v152
	v_add_f32_e32 v83, v91, v153
	v_add_f32_e32 v76, v76, v92
	v_add_f32_e32 v77, v77, v93
	s_waitcnt lgkmcnt(2)
	v_mfma_f32_32x32x16_bf16 v[0:15], v[36:39], v[40:43], v[0:15]
	v_add_f32_e64 v36, v82, v44
	v_add_f32_e64 v37, v83, v45
	v_add_f32_e64 v48, v64, v68
	v_add_f32_e64 v49, v65, v69
	v_add_f32_e64 v36, v76, v36
	v_add_f32_e64 v37, v77, v37
	v_add_f32_e32 v50, v66, v72
	v_add_f32_e32 v51, v67, v73
	v_add_f32_e32 v36, v48, v36
	v_add_f32_e32 v37, v49, v37
	v_add_f32_e32 v64, v70, v74
	v_add_f32_e32 v65, v71, v75
	v_add_f32_e32 v36, v50, v36
	v_add_f32_e32 v37, v51, v37
	s_waitcnt lgkmcnt(0)
	v_mfma_f32_32x32x16_bf16 v[16:31], v[32:35], v[40:43], v[16:31]
	v_add_f32_e64 v36, v64, v36
	v_add_f32_e64 v37, v65, v37
	v_add_f32_e32 v36, v178, v36
	v_add_f32_e32 v178, v36, v37
	s_branch .LBB0_1072
